# grid barrier: agent-scope acquire (buffer_inv sc1) moved before the release wait (non-leaders after arrival, XCD leader behind its write-back), none after release
# speedup vs baseline: 1.0086x; 1.0086x over previous
.Lxb0_194:
	s_or_b64 exec, exec, s[12:13]
	v_cvt_f32_u32_e32 v4, v2
	s_waitcnt vmcnt(0)
	v_readfirstlane_b32 s0, v3
	v_sub_u32_e32 v3, 0, v2
	v_rcp_iflag_f32_e32 v4, v4
	v_add_u32_e32 v5, s0, v1
	v_mul_f32_e32 v4, 0x4f7ffffe, v4
	v_cvt_u32_f32_e32 v4, v4
	v_mul_lo_u32 v1, v3, v4
	v_mul_hi_u32 v1, v4, v1
	v_add_u32_e32 v1, v4, v1
	v_mul_hi_u32 v1, v5, v1
	v_mul_lo_u32 v3, v1, v2
	v_sub_u32_e32 v3, v5, v3
	v_add_u32_e32 v4, 1, v1
	v_cmp_ge_u32_e32 vcc, v3, v2
	s_nop 1
	v_cndmask_b32_e32 v1, v1, v4, vcc
	v_sub_u32_e32 v4, v3, v2
	v_cndmask_b32_e32 v3, v3, v4, vcc
	v_add_u32_e32 v4, 1, v1
	v_cmp_ge_u32_e32 vcc, v3, v2
	v_add_u32_e32 v3, 1, v5
	s_nop 0
	v_cndmask_b32_e32 v1, v1, v4, vcc
	v_mul_lo_u32 v4, v2, v1
	v_add_u32_e32 v2, v4, v2
	v_cmp_ne_u32_e32 vcc, v3, v2
	s_and_saveexec_b64 s[0:1], vcc
	s_xor_b64 s[10:11], exec, s[0:1]
	s_cbranch_execz .Lxb0_208
	s_waitcnt lgkmcnt(0)
	buffer_inv sc1
	v_mov_b32_e32 v0, 0x2000
	global_load_dword v0, v0, s[8:9] offset:1024 sc1
	s_add_u32 s16, s8, 0x2400
	s_addc_u32 s17, s9, 0
	s_waitcnt vmcnt(0)
	v_cmp_eq_u32_e32 vcc, v0, v1
	s_and_saveexec_b64 s[12:13], vcc
	s_cbranch_execz .Lxb0_207
	s_add_u32 s14, s54, 0x4200
	s_addc_u32 s15, s55, 0
	s_mov_b32 s0, 1
	s_mov_b64 s[20:21], 0
	v_mov_b32_e32 v0, 0
	s_branch .Lxb0_198

.Lxb0_207:
	s_or_b64 exec, exec, s[12:13]
	s_waitcnt vmcnt(0)
	s_waitcnt vmcnt(0)
.Lxb0_208:
	s_andn2_saveexec_b64 s[0:1], s[10:11]
	s_cbranch_execz .Lxb0_228
	s_mov_b64 s[10:11], exec
	buffer_wbl2 sc1
	s_waitcnt lgkmcnt(0)
	s_waitcnt vmcnt(0)
	buffer_inv sc1
	v_mbcnt_lo_u32_b32 v1, s10, 0
	v_mbcnt_hi_u32_b32 v1, s11, v1
	v_cmp_eq_u32_e32 vcc, 0, v1
	s_and_saveexec_b64 s[12:13], vcc
	s_cbranch_execz .Lxb0_211
	s_bcnt1_i32_b64 s0, s[10:11]
	v_mov_b32_e32 v2, 0x7000
	v_mov_b32_e32 v3, s0
	global_atomic_add v2, v2, v3, s[54:55] offset:1024 sc0

.Lxb0_225:
	s_or_b64 exec, exec, s[10:11]
	s_mov_b64 s[10:11], exec
	v_mbcnt_lo_u32_b32 v0, s10, 0
	v_mbcnt_hi_u32_b32 v0, s11, v0
	v_cmp_eq_u32_e32 vcc, 0, v0
	s_waitcnt vmcnt(0)
	s_and_saveexec_b64 s[12:13], vcc
	s_cbranch_execz .Lxb0_227
	s_bcnt1_i32_b64 s0, s[10:11]
	v_mov_b32_e32 v0, 0x2000
	v_mov_b32_e32 v1, s0
	global_atomic_add v0, v1, s[8:9] offset:1024

.LBB0_256:
	s_or_b64 exec, exec, s[12:13]
	v_cvt_f32_u32_e32 v4, v2
	s_waitcnt vmcnt(0)
	v_readfirstlane_b32 s0, v3
	v_sub_u32_e32 v3, 0, v2
	v_rcp_iflag_f32_e32 v4, v4
	v_add_u32_e32 v5, s0, v1
	v_mul_f32_e32 v4, 0x4f7ffffe, v4
	v_cvt_u32_f32_e32 v4, v4
	v_mul_lo_u32 v1, v3, v4
	v_mul_hi_u32 v1, v4, v1
	v_add_u32_e32 v1, v4, v1
	v_mul_hi_u32 v1, v5, v1
	v_mul_lo_u32 v3, v1, v2
	v_sub_u32_e32 v3, v5, v3
	v_add_u32_e32 v4, 1, v1
	v_cmp_ge_u32_e32 vcc, v3, v2
	s_nop 1
	v_cndmask_b32_e32 v1, v1, v4, vcc
	v_sub_u32_e32 v4, v3, v2
	v_cndmask_b32_e32 v3, v3, v4, vcc
	v_add_u32_e32 v4, 1, v1
	v_cmp_ge_u32_e32 vcc, v3, v2
	v_add_u32_e32 v3, 1, v5
	s_nop 0
	v_cndmask_b32_e32 v1, v1, v4, vcc
	v_mul_lo_u32 v4, v2, v1
	v_add_u32_e32 v2, v4, v2
	v_cmp_ne_u32_e32 vcc, v3, v2
	s_and_saveexec_b64 s[0:1], vcc
	s_xor_b64 s[10:11], exec, s[0:1]
	s_cbranch_execz .LBB0_270
	s_waitcnt lgkmcnt(0)
	buffer_inv sc1
	v_mov_b32_e32 v0, 0x2000
	global_load_dword v0, v0, s[6:7] offset:1024 sc1
	s_add_u32 s16, s6, 0x2400
	s_addc_u32 s17, s7, 0
	s_waitcnt vmcnt(0)
	v_cmp_eq_u32_e32 vcc, v0, v1
	s_and_saveexec_b64 s[12:13], vcc
	s_cbranch_execz .LBB0_269
	s_add_u32 s14, s54, 0x4200
	s_addc_u32 s15, s55, 0
	s_mov_b32 s0, 1
	s_mov_b64 s[18:19], 0
	v_mov_b32_e32 v0, 0
	s_branch .LBB0_260

.LBB0_287:
	s_or_b64 exec, exec, s[10:11]
	s_mov_b64 s[10:11], exec
	v_mbcnt_lo_u32_b32 v0, s10, 0
	v_mbcnt_hi_u32_b32 v0, s11, v0
	v_cmp_eq_u32_e32 vcc, 0, v0
	s_waitcnt vmcnt(0)
	s_and_saveexec_b64 s[12:13], vcc
	s_cbranch_execz .LBB0_289
	s_bcnt1_i32_b64 s0, s[10:11]
	v_mov_b32_e32 v0, 0x2000
	v_mov_b32_e32 v1, s0
	global_atomic_add v0, v1, s[6:7] offset:1024

.LBB0_331:
	s_or_b64 exec, exec, s[12:13]
	v_cvt_f32_u32_e32 v4, v2
	s_waitcnt vmcnt(0)
	v_readfirstlane_b32 s0, v3
	v_sub_u32_e32 v3, 0, v2
	v_rcp_iflag_f32_e32 v4, v4
	v_add_u32_e32 v5, s0, v1
	v_mul_f32_e32 v4, 0x4f7ffffe, v4
	v_cvt_u32_f32_e32 v4, v4
	v_mul_lo_u32 v1, v3, v4
	v_mul_hi_u32 v1, v4, v1
	v_add_u32_e32 v1, v4, v1
	v_mul_hi_u32 v1, v5, v1
	v_mul_lo_u32 v3, v1, v2
	v_sub_u32_e32 v3, v5, v3
	v_add_u32_e32 v4, 1, v1
	v_cmp_ge_u32_e32 vcc, v3, v2
	s_nop 1
	v_cndmask_b32_e32 v1, v1, v4, vcc
	v_sub_u32_e32 v4, v3, v2
	v_cndmask_b32_e32 v3, v3, v4, vcc
	v_add_u32_e32 v4, 1, v1
	v_cmp_ge_u32_e32 vcc, v3, v2
	v_add_u32_e32 v3, 1, v5
	s_nop 0
	v_cndmask_b32_e32 v1, v1, v4, vcc
	v_mul_lo_u32 v4, v2, v1
	v_add_u32_e32 v2, v4, v2
	v_cmp_ne_u32_e32 vcc, v3, v2
	s_and_saveexec_b64 s[0:1], vcc
	s_xor_b64 s[10:11], exec, s[0:1]
	s_cbranch_execz .LBB0_345
	s_waitcnt lgkmcnt(0)
	buffer_inv sc1
	v_mov_b32_e32 v0, 0x2000
	global_load_dword v0, v0, s[8:9] offset:1024 sc1
	s_add_u32 s16, s8, 0x2400
	s_addc_u32 s17, s9, 0
	s_waitcnt vmcnt(0)
	v_cmp_eq_u32_e32 vcc, v0, v1
	s_and_saveexec_b64 s[12:13], vcc
	s_cbranch_execz .LBB0_344
	s_add_u32 s14, s54, 0x4200
	s_addc_u32 s15, s55, 0
	s_mov_b32 s0, 1
	s_mov_b64 s[18:19], 0
	v_mov_b32_e32 v0, 0
	s_branch .LBB0_335

.LBB0_735:
	s_or_b64 exec, exec, s[14:15]
	v_cvt_f32_u32_e32 v4, v2
	s_waitcnt vmcnt(0)
	v_readfirstlane_b32 s0, v3
	v_sub_u32_e32 v3, 0, v2
	v_rcp_iflag_f32_e32 v4, v4
	v_add_u32_e32 v5, s0, v1
	v_mul_f32_e32 v4, 0x4f7ffffe, v4
	v_cvt_u32_f32_e32 v4, v4
	v_mul_lo_u32 v1, v3, v4
	v_mul_hi_u32 v1, v4, v1
	v_add_u32_e32 v1, v4, v1
	v_mul_hi_u32 v1, v5, v1
	v_mul_lo_u32 v3, v1, v2
	v_sub_u32_e32 v3, v5, v3
	v_add_u32_e32 v4, 1, v1
	v_cmp_ge_u32_e32 vcc, v3, v2
	s_nop 1
	v_cndmask_b32_e32 v1, v1, v4, vcc
	v_sub_u32_e32 v4, v3, v2
	v_cndmask_b32_e32 v3, v3, v4, vcc
	v_add_u32_e32 v4, 1, v1
	v_cmp_ge_u32_e32 vcc, v3, v2
	v_add_u32_e32 v3, 1, v5
	s_nop 0
	v_cndmask_b32_e32 v1, v1, v4, vcc
	v_mul_lo_u32 v4, v2, v1
	v_add_u32_e32 v2, v4, v2
	v_cmp_ne_u32_e32 vcc, v3, v2
	s_and_saveexec_b64 s[0:1], vcc
	s_xor_b64 s[12:13], exec, s[0:1]
	s_cbranch_execz .LBB0_749
	s_waitcnt lgkmcnt(0)
	buffer_inv sc1
	v_mov_b32_e32 v0, 0x2000
	global_load_dword v0, v0, s[10:11] offset:1024 sc1
	s_add_u32 s18, s10, 0x2400
	s_addc_u32 s19, s11, 0
	s_waitcnt vmcnt(0)
	v_cmp_eq_u32_e32 vcc, v0, v1
	s_and_saveexec_b64 s[14:15], vcc
	s_cbranch_execz .LBB0_748
	s_add_u32 s16, s54, 0x4200
	s_addc_u32 s17, s55, 0
	s_mov_b32 s0, 1
	s_mov_b64 s[20:21], 0
	v_mov_b32_e32 v0, 0
	s_branch .LBB0_739

.LBB0_748:
	s_or_b64 exec, exec, s[14:15]
	s_waitcnt vmcnt(0)
	s_waitcnt vmcnt(0)
.LBB0_749:
	s_andn2_saveexec_b64 s[0:1], s[12:13]
	s_cbranch_execz .LBB0_769
	s_mov_b64 s[12:13], exec
	buffer_wbl2 sc1
	s_waitcnt lgkmcnt(0)
	s_waitcnt vmcnt(0)
	buffer_inv sc1
	v_mbcnt_lo_u32_b32 v1, s12, 0
	v_mbcnt_hi_u32_b32 v1, s13, v1
	v_cmp_eq_u32_e32 vcc, 0, v1
	s_and_saveexec_b64 s[14:15], vcc
	s_cbranch_execz .LBB0_752
	s_bcnt1_i32_b64 s0, s[12:13]
	v_mov_b32_e32 v2, 0x7000
	v_mov_b32_e32 v3, s0
	global_atomic_add v2, v2, v3, s[54:55] offset:1024 sc0

.LBB0_766:
	s_or_b64 exec, exec, s[12:13]
	s_mov_b64 s[12:13], exec
	v_mbcnt_lo_u32_b32 v0, s12, 0
	v_mbcnt_hi_u32_b32 v0, s13, v0
	v_cmp_eq_u32_e32 vcc, 0, v0
	s_waitcnt vmcnt(0)
	s_and_saveexec_b64 s[14:15], vcc
	s_cbranch_execz .LBB0_768
	s_bcnt1_i32_b64 s0, s[12:13]
	v_mov_b32_e32 v0, 0x2000
	v_mov_b32_e32 v1, s0
	global_atomic_add v0, v1, s[10:11] offset:1024

.LBB0_1040:
	s_or_b64 exec, exec, s[10:11]
	v_cvt_f32_u32_e32 v4, v2
	s_waitcnt vmcnt(0)
	v_readfirstlane_b32 s3, v3
	v_sub_u32_e32 v3, 0, v2
	v_rcp_iflag_f32_e32 v4, v4
	v_add_u32_e32 v5, s3, v1
	v_mul_f32_e32 v4, 0x4f7ffffe, v4
	v_cvt_u32_f32_e32 v4, v4
	v_mul_lo_u32 v1, v3, v4
	v_mul_hi_u32 v1, v4, v1
	v_add_u32_e32 v1, v4, v1
	v_mul_hi_u32 v1, v5, v1
	v_mul_lo_u32 v3, v1, v2
	v_sub_u32_e32 v3, v5, v3
	v_add_u32_e32 v4, 1, v1
	v_cmp_ge_u32_e32 vcc, v3, v2
	s_nop 1
	v_cndmask_b32_e32 v1, v1, v4, vcc
	v_sub_u32_e32 v4, v3, v2
	v_cndmask_b32_e32 v3, v3, v4, vcc
	v_add_u32_e32 v4, 1, v1
	v_cmp_ge_u32_e32 vcc, v3, v2
	v_add_u32_e32 v3, 1, v5
	s_nop 0
	v_cndmask_b32_e32 v1, v1, v4, vcc
	v_mul_lo_u32 v4, v2, v1
	v_add_u32_e32 v2, v4, v2
	v_cmp_ne_u32_e32 vcc, v3, v2
	s_and_saveexec_b64 s[8:9], vcc
	s_xor_b64 s[8:9], exec, s[8:9]
	s_cbranch_execz .LBB0_1054
	s_waitcnt lgkmcnt(0)
	buffer_inv sc1
	v_mov_b32_e32 v0, 0x2000
	global_load_dword v0, v0, s[0:1] offset:1024 sc1
	s_add_u32 s14, s0, 0x2400
	s_addc_u32 s15, s1, 0
	s_waitcnt vmcnt(0)
	v_cmp_eq_u32_e32 vcc, v0, v1
	s_and_saveexec_b64 s[10:11], vcc
	s_cbranch_execz .LBB0_1053
	s_add_u32 s12, s54, 0x4200
	s_addc_u32 s13, s55, 0
	s_mov_b32 s3, 1
	s_mov_b64 s[16:17], 0
	v_mov_b32_e32 v0, 0
	s_branch .LBB0_1044

.LBB0_1053:
	s_or_b64 exec, exec, s[10:11]
	s_waitcnt vmcnt(0)
	s_waitcnt vmcnt(0)
.LBB0_1054:
	s_andn2_saveexec_b64 s[8:9], s[8:9]
	s_cbranch_execz .LBB0_1074
	s_mov_b64 s[8:9], exec
	buffer_wbl2 sc1
	s_waitcnt lgkmcnt(0)
	s_waitcnt vmcnt(0)
	buffer_inv sc1
	v_mbcnt_lo_u32_b32 v1, s8, 0
	v_mbcnt_hi_u32_b32 v1, s9, v1
	v_cmp_eq_u32_e32 vcc, 0, v1
	s_and_saveexec_b64 s[10:11], vcc
	s_cbranch_execz .LBB0_1057
	s_bcnt1_i32_b64 s3, s[8:9]
	v_mov_b32_e32 v2, 0x7000
	v_mov_b32_e32 v3, s3
	global_atomic_add v2, v2, v3, s[54:55] offset:1024 sc0

.LBB0_1071:
	s_or_b64 exec, exec, s[8:9]
	s_mov_b64 s[8:9], exec
	v_mbcnt_lo_u32_b32 v0, s8, 0
	v_mbcnt_hi_u32_b32 v0, s9, v0
	v_cmp_eq_u32_e32 vcc, 0, v0
	s_waitcnt vmcnt(0)
	s_and_saveexec_b64 s[10:11], vcc
	s_cbranch_execz .LBB0_1073
	s_bcnt1_i32_b64 s3, s[8:9]
	v_mov_b32_e32 v0, 0x2000
	v_mov_b32_e32 v1, s3
	global_atomic_add v0, v1, s[0:1] offset:1024
